# attention phase: one static s_setprio 1 for waves 4-7 at phase entry, all per-section priority flips inside the attention tile loops deleted; otherwise v19
# speedup vs baseline: 1.0001x; 1.0001x over previous
; #define LAS __attribute__((address_space(3)))
; DI int tid_fresh() { int t = threadIdx.x; asm volatile("" : "+v"(t)); return t; }
; DI void phase_attention(KParams P, LAS unsigned char* lds) {
;   const bf16_t* qkva = P->X; const bf16_t* lat = P->X + (size_t)T_TOK * 3072; const bf16_t* qb_ = lat + (size_t)T_TOK * 1536; const bf16_t* kv = qb_ + (size_t)T_TOK * 1536;
;   const int lane = tid_fresh() & 63, wid = tid_fresh() >> 6, r = lane & 31, h = lane >> 5;
;   float lam;
;   { const float s1 = wave_sum(P->lq1[lane] * P->lk1[lane]), s2 = wave_sum(P->lq2[lane] * P->lk2[lane]); lam = __expf(s1) - __expf(s2) + 0.2f; }
;   const int G = gridDim.x;
;   const int vb = (int)blockIdx.x;
;   const float LOG2E = 1.4426950408889634f;
;     ...
;   for (int it = vb; it < 256; it += G) {
.LBB0_90:
	s_andn2_b64 vcc, exec, s[4:5]
	s_cbranch_vccnz .LBB0_149
	v_readlane_b32 s4, v250, 25
	s_cmp_eq_u32 s4, 5
	v_readlane_b32 s5, v250, 26
	s_cbranch_scc0 .LBB0_149
	v_mov_b32_e32 v0, v163
	v_mov_b32_e32 v2, v163
	s_waitcnt lgkmcnt(0)
	s_load_dwordx8 s[40:47], s[0:1], 0x30
	v_and_b32_e32 v3, 63, v0
	v_lshlrev_b32_e32 v3, 2, v3
	s_waitcnt lgkmcnt(0)
	global_load_dword v4, v3, s[40:41]
	global_load_dword v5, v3, s[42:43]
	global_load_dword v6, v3, s[44:45]
	s_nop 0
	global_load_dword v3, v3, s[46:47]
	v_cmp_lt_i32_e32 vcc, v193, v192
	v_readlane_b32 s4, v251, 7
	v_readlane_b32 s5, v251, 8
	v_cndmask_b32_e32 v7, v191, v193, vcc
	v_lshlrev_b32_e32 v151, 2, v7
	v_cmp_lt_i32_e32 vcc, v194, v192
	s_waitcnt vmcnt(0)
	v_mul_f32_e32 v7, v4, v5
	ds_bpermute_b32 v7, v151, v7
	v_mul_f32_e32 v8, v6, v3
	ds_bpermute_b32 v8, v151, v8
	v_cndmask_b32_e32 v9, v191, v194, vcc
	v_lshlrev_b32_e32 v9, 2, v9
	s_waitcnt lgkmcnt(1)
	v_fmac_f32_e32 v7, v4, v5
	v_cmp_lt_i32_e32 vcc, v195, v192
	s_waitcnt lgkmcnt(0)
	v_fmac_f32_e32 v8, v6, v3
	ds_bpermute_b32 v3, v9, v7
	ds_bpermute_b32 v4, v9, v8
	v_cndmask_b32_e32 v5, v191, v195, vcc
	v_lshlrev_b32_e32 v5, 2, v5
	v_cmp_lt_i32_e32 vcc, v196, v192
	s_waitcnt lgkmcnt(1)
	v_add_f32_e32 v3, v7, v3
	s_waitcnt lgkmcnt(0)
	v_add_f32_e32 v4, v8, v4
	ds_bpermute_b32 v6, v5, v3
	ds_bpermute_b32 v5, v5, v4
	v_cndmask_b32_e32 v7, v191, v196, vcc
	v_lshlrev_b32_e32 v7, 2, v7
	v_cmp_lt_i32_e32 vcc, v197, v192
	s_waitcnt lgkmcnt(1)
	v_add_f32_e32 v3, v3, v6
	s_waitcnt lgkmcnt(0)
	v_add_f32_e32 v4, v4, v5
	ds_bpermute_b32 v5, v7, v3
	ds_bpermute_b32 v6, v7, v4
	v_cndmask_b32_e32 v7, v191, v197, vcc
	v_lshlrev_b32_e32 v7, 2, v7
	v_cmp_lt_i32_e32 vcc, v198, v192
	s_waitcnt lgkmcnt(1)
	v_add_f32_e32 v3, v3, v5
	s_waitcnt lgkmcnt(0)
	v_add_f32_e32 v4, v4, v6
	ds_bpermute_b32 v5, v7, v3
	ds_bpermute_b32 v6, v7, v4
	v_cndmask_b32_e32 v7, v191, v198, vcc
	v_lshlrev_b32_e32 v7, 2, v7
	s_andn2_b64 vcc, exec, s[4:5]
	s_waitcnt lgkmcnt(1)
	v_add_f32_e32 v3, v3, v5
	s_waitcnt lgkmcnt(0)
	v_add_f32_e32 v4, v4, v6
	ds_bpermute_b32 v5, v7, v3
	ds_bpermute_b32 v6, v7, v4
	s_cbranch_vccnz .LBB0_149
	s_waitcnt lgkmcnt(1)
	v_add_f32_e32 v3, v3, v5
	s_waitcnt lgkmcnt(0)
	v_add_f32_e32 v4, v4, v6
	v_mul_f32_e32 v3, 0x3fb8aa3b, v3
	v_mul_f32_e32 v4, 0x3fb8aa3b, v4
	v_exp_f32_e32 v3, v3
	v_exp_f32_e32 v4, v4
	s_load_dword s3, s[68:69], 0x0
	v_ashrrev_i32_e32 v2, 1, v2
	s_movk_i32 s4, 0xffe0
	v_sub_f32_e32 v3, v3, v4
	v_add_f32_e32 v148, 0x3e4ccccd, v3
	v_lshrrev_b32_e32 v3, 3, v0
	v_and_b32_e32 v150, 4, v3
	v_bfi_b32 v165, s4, v2, v0
	v_mov_b32_e32 v149, v148
	v_readfirstlane_b32 s4, v163
	s_nop 3
	s_lshr_b32 s4, s4, 6
	s_cmp_ge_u32 s4, 4
	s_cbranch_scc0 .Lprio_att
	s_setprio 1
.Lprio_att:
	v_readlane_b32 s17, v251, 0
	s_waitcnt lgkmcnt(0)
	s_cmp_lg_u32 s3, 0x100
	s_cbranch_scc1 .Lxr_a
	s_and_b32 s4, s17, 7
	s_lshl_b32 s4, s4, 5
	s_lshr_b32 s5, s17, 3
	s_or_b32 s17, s4, s5

; #define LAS __attribute__((address_space(3)))
; template <int DK>
; DI void attn_pass(const AttnSrc& s, const int q0, const float sc, LAS unsigned char* lds, f32x16 (&O)[4]) {
;     ...
;     if (t + DPF < NT) issue(t + DPF, pbuf);
;     if (64 * t <= qw0 + 31) {
;       LAS unsigned char* Kb = lds + buf * STG; LAS unsigned char* Vb = lds + buf * STG + KSZ;
;       f32x16 p0, p1;
;       constexpr int GS = (DK == 64) ? 4 : 2, NG = NS / GS;
;       bf16x8 kfa[2][GS], kfb[2][GS];
;       auto kload = [&](int g, int slot) {
; #pragma unroll
;         for (int j = 0; j < GS; ++j) { const int lc = 2 * (g * GS + j) + h; const int ph = (DK == 64) ? (lc ^ kx) : ((lc & ~7) | ((lc & 7) ^ kx));
;           kfa[slot][j] = *(const LAS bf16x8*)(Kb + krow + ph * 16); kfb[slot][j] = *(const LAS bf16x8*)(Kb + krow + 32 * ROWB + ph * 16); }
;       };
;       kload(0, 0);
; #pragma unroll
;       for (int g = 0; g < NG; ++g) {
;         if (g + 1 < NG) kload(g + 1, (g + 1) & 1);
;         __builtin_amdgcn_s_setprio(1);
; #pragma unroll
;         for (int j = 0; j < GS; ++j) {
;           if (g == 0 && j == 0) {
;             if (REL) {
;               p0 = __builtin_amdgcn_mfma_f32_32x32x16_bf16(kfa[0][0], qf[0], negm, 0, 0, 0);
;               p1 = __builtin_amdgcn_mfma_f32_32x32x16_bf16(kfb[0][0], qf[0], negm, 0, 0, 0);
;             } else {
;               f32x16 z;
; #pragma unroll
;               for (int jj = 0; jj < 16; ++jj) z[jj] = 0.f;
;               p0 = __builtin_amdgcn_mfma_f32_32x32x16_bf16(kfa[0][0], qf[0], z, 0, 0, 0);
;               p1 = __builtin_amdgcn_mfma_f32_32x32x16_bf16(kfb[0][0], qf[0], z, 0, 0, 0);
;             }
;           } else {
;             p0 = __builtin_amdgcn_mfma_f32_32x32x16_bf16(kfa[g & 1][j], qf[g * GS + j], p0, 0, 0, 0);
;             p1 = __builtin_amdgcn_mfma_f32_32x32x16_bf16(kfb[g & 1][j], qf[g * GS + j], p1, 0, 0, 0);
;           }
;         }
;         __builtin_amdgcn_s_setprio(0);
;       }
.LBB0_112:
	s_sub_i32 s18, s53, 63
	s_cmp_gt_i32 s18, s56
	s_cbranch_scc1 .Ln64_skip
	s_mul_i32 s18, s55, 0x6000
	s_add_i32 s18, s18, 0
	v_add_u32_e32 v0, s18, v213
	v_add_u32_e32 v6, v0, v218
	v_add_u32_e32 v15, v0, v219
	ds_read_b128 v[2:5], v6
	ds_read_b128 v[6:9], v6 offset:4096
	ds_read_b128 v[10:13], v15
	ds_read_b128 v[144:147], v15 offset:4096
	v_add_u32_e32 v15, v0, v220
	v_add_u32_e32 v0, v0, v221
	ds_read_b128 v[230:233], v15
	ds_read_b128 v[234:237], v15 offset:4096
	ds_read_b128 v[238:241], v0
	ds_read_b128 v[242:245], v0 offset:4096
	s_waitcnt lgkmcnt(6)
	v_mfma_f32_32x32x16_bf16 v[112:127], v[2:5], v[128:131], v[80:95]
	v_mfma_f32_32x32x16_bf16 v[96:111], v[6:9], v[128:131], v[80:95]
	s_waitcnt lgkmcnt(4)
	v_mfma_f32_32x32x16_bf16 v[112:127], v[10:13], v[132:135], v[112:127]
	v_mfma_f32_32x32x16_bf16 v[96:111], v[144:147], v[132:135], v[96:111]
	s_waitcnt lgkmcnt(2)
	v_mfma_f32_32x32x16_bf16 v[112:127], v[230:233], v[136:139], v[112:127]
	v_mfma_f32_32x32x16_bf16 v[96:111], v[234:237], v[136:139], v[96:111]
	s_waitcnt lgkmcnt(0)
	v_mfma_f32_32x32x16_bf16 v[112:127], v[238:241], v[140:143], v[112:127]
	v_mfma_f32_32x32x16_bf16 v[96:111], v[242:245], v[140:143], v[96:111]
	v_add3_u32 v0, s18, v214, v215
	v_add3_u32 v15, v0, v216, v217
	v_add_u32_e32 v246, v15, v222
	v_add_u32_e32 v247, v15, v224
	v_add_u32_e32 v248, v15, v225
	v_add_u32_e32 v249, v15, v226
	s_cmp_ge_u32 s54, s41
	s_cbranch_scc1 .Ln64_dmadone
	s_mul_i32 s18, s58, 0x6000
	v_lshl_add_u64 v[2:3], v[170:171], 0, s[14:15]
	s_add_i32 s19, s18, s46
	s_mov_b32 s62, m0
	s_mov_b32 m0, s19
	s_nop 0
	global_load_lds_dwordx4 v[2:3], off
	s_mov_b32 m0, s62
	v_lshl_add_u64 v[2:3], v[168:169], 0, s[14:15]
	s_add_i32 s19, s18, s47
	s_mov_b32 s62, m0
	s_mov_b32 m0, s19
	s_nop 0
	global_load_lds_dwordx4 v[2:3], off
	s_mov_b32 m0, s62
	v_lshl_add_u64 v[2:3], v[166:167], 0, s[14:15]
	s_add_i32 s18, s18, s52
	s_mov_b32 s19, m0
	s_mov_b32 m0, s18
	s_nop 0
	global_load_lds_dwordx4 v[2:3], off
	s_mov_b32 m0, s19

; DI unsigned cvt_pk_bf16(float lo, float hi) { unsigned r; asm volatile("v_cvt_pk_bf16_f32 %0, %1, %2" : "=v"(r) : "v"(lo), "v"(hi)); return r; }
; template <int DK>
; DI void attn_pass(const AttnSrc& s, const int q0, const float sc, LAS unsigned char* lds, f32x16 (&O)[4]) {
;     ...
;         for (int j = 0; j < 16; ++j) { p0[j] = __builtin_amdgcn_exp2f(p0[j]); p1[j] = __builtin_amdgcn_exp2f(p1[j]); rs += p0[j] + p1[j]; }
;       } else {
;         const float cand = mx * sc;
;         const bool grow = cand > mrun + 8.f;
;         if (__builtin_amdgcn_ballot_w64(grow) != 0ull) {
;           const float mnew = grow ? cand : mrun;
;           const float alpha = __builtin_amdgcn_exp2f(mrun - mnew);
;           mrun = mnew; lrun *= alpha;
; #pragma unroll
;           for (int i = 0; i < 4; ++i)
; #pragma unroll
;             for (int j = 0; j < 16; ++j) O[i][j] *= alpha;
;         }
; #pragma unroll
;         for (int j = 0; j < 16; ++j) { p0[j] = __builtin_amdgcn_exp2f(p0[j] * sc - mrun); p1[j] = __builtin_amdgcn_exp2f(p1[j] * sc - mrun); rs += p0[j] + p1[j]; }
;       }
;       lrun += rs;
;       bf16x8 pb[4];
;       { u32x4 w;
;         w.x = cvt_pk_bf16(p0[0], p0[1]); w.y = cvt_pk_bf16(p0[2], p0[3]); w.z = cvt_pk_bf16(p0[4], p0[5]); w.w = cvt_pk_bf16(p0[6], p0[7]); pb[0] = __builtin_bit_cast(bf16x8, w);
;         w.x = cvt_pk_bf16(p0[8], p0[9]); w.y = cvt_pk_bf16(p0[10], p0[11]); w.z = cvt_pk_bf16(p0[12], p0[13]); w.w = cvt_pk_bf16(p0[14], p0[15]); pb[1] = __builtin_bit_cast(bf16x8, w);
;         w.x = cvt_pk_bf16(p1[0], p1[1]); w.y = cvt_pk_bf16(p1[2], p1[3]); w.z = cvt_pk_bf16(p1[4], p1[5]); w.w = cvt_pk_bf16(p1[6], p1[7]); pb[2] = __builtin_bit_cast(bf16x8, w);
;         w.x = cvt_pk_bf16(p1[8], p1[9]); w.y = cvt_pk_bf16(p1[10], p1[11]); w.z = cvt_pk_bf16(p1[12], p1[13]); w.w = cvt_pk_bf16(p1[14], p1[15]); pb[3] = __builtin_bit_cast(bf16x8, w); }
; #pragma unroll
;       for (int vt = 0; vt < 4; ++vt) {
;         if (vt + 1 < 4) vload(vt + 1, (vt + 1) & 1);
;         __builtin_amdgcn_s_setprio(1);
; #pragma unroll
;         for (int ks = 0; ks < 4; ++ks) O[vt] = __builtin_amdgcn_mfma_f32_32x32x16_bf16(vf[vt & 1][ks], pb[ks], O[vt], 0, 0, 0);
;         __builtin_amdgcn_s_setprio(0);
;       }
.Ln64_exp:
	v_exp_f32_e32 v112, v112
	v_exp_f32_e32 v113, v113
	v_exp_f32_e32 v114, v114
	v_exp_f32_e32 v115, v115
	v_exp_f32_e32 v116, v116
	v_exp_f32_e32 v117, v117
	v_exp_f32_e32 v118, v118
	v_exp_f32_e32 v119, v119
	v_add_f32_e32 v0, v112, v113
	v_add_f32_e32 v15, v114, v115
	v_add_f32_e32 v0, v0, v116
	v_add_f32_e32 v15, v15, v117
	v_add_f32_e32 v0, v0, v118
	v_add_f32_e32 v15, v15, v119
	v_cvt_pk_bf16_f32 v112, v112, v113
	v_cvt_pk_bf16_f32 v113, v114, v115
	v_cvt_pk_bf16_f32 v114, v116, v117
	v_cvt_pk_bf16_f32 v115, v118, v119
	ds_read_b64_tr_b16 v[230:231], v246 offset:12288
	ds_read_b64_tr_b16 v[232:233], v246 offset:14336
	ds_read_b64_tr_b16 v[234:235], v247 offset:12288
	ds_read_b64_tr_b16 v[236:237], v247 offset:14336
	ds_read_b64_tr_b16 v[238:239], v248 offset:12288
	ds_read_b64_tr_b16 v[240:241], v248 offset:14336
	ds_read_b64_tr_b16 v[242:243], v249 offset:12288
	ds_read_b64_tr_b16 v[244:245], v249 offset:14336
	s_waitcnt lgkmcnt(14)
	v_mfma_f32_32x32x16_bf16 v[64:79], v[2:5], v[112:115], v[64:79]
	s_waitcnt lgkmcnt(12)
	v_mfma_f32_32x32x16_bf16 v[48:63], v[6:9], v[112:115], v[48:63]
	s_waitcnt lgkmcnt(10)
	v_mfma_f32_32x32x16_bf16 v[32:47], v[10:13], v[112:115], v[32:47]
	s_waitcnt lgkmcnt(8)
	v_mfma_f32_32x32x16_bf16 v[16:31], v[144:147], v[112:115], v[16:31]
	v_exp_f32_e32 v120, v120
	v_exp_f32_e32 v121, v121
	v_exp_f32_e32 v122, v122
	v_exp_f32_e32 v123, v123
	v_exp_f32_e32 v124, v124
	v_exp_f32_e32 v125, v125
	v_exp_f32_e32 v126, v126
	v_exp_f32_e32 v127, v127
	v_add_f32_e32 v0, v0, v120
	v_add_f32_e32 v15, v15, v121
	v_add_f32_e32 v0, v0, v122
	v_add_f32_e32 v15, v15, v123
	v_add_f32_e32 v0, v0, v124
	v_add_f32_e32 v15, v15, v125
	v_add_f32_e32 v0, v0, v126
	v_add_f32_e32 v15, v15, v127
	v_cvt_pk_bf16_f32 v116, v120, v121
	v_cvt_pk_bf16_f32 v117, v122, v123
	v_cvt_pk_bf16_f32 v118, v124, v125
	v_cvt_pk_bf16_f32 v119, v126, v127
	ds_read_b64_tr_b16 v[2:3], v246 offset:16384
	ds_read_b64_tr_b16 v[4:5], v246 offset:18432
	ds_read_b64_tr_b16 v[6:7], v247 offset:16384
	ds_read_b64_tr_b16 v[8:9], v247 offset:18432
	ds_read_b64_tr_b16 v[10:11], v248 offset:16384
	ds_read_b64_tr_b16 v[12:13], v248 offset:18432
	ds_read_b64_tr_b16 v[144:145], v249 offset:16384
	ds_read_b64_tr_b16 v[146:147], v249 offset:18432
	s_waitcnt lgkmcnt(14)
	v_mfma_f32_32x32x16_bf16 v[64:79], v[230:233], v[116:119], v[64:79]
	s_waitcnt lgkmcnt(12)
	v_mfma_f32_32x32x16_bf16 v[48:63], v[234:237], v[116:119], v[48:63]
	s_waitcnt lgkmcnt(10)
	v_mfma_f32_32x32x16_bf16 v[32:47], v[238:241], v[116:119], v[32:47]
	s_waitcnt lgkmcnt(8)
	v_mfma_f32_32x32x16_bf16 v[16:31], v[242:245], v[116:119], v[16:31]
	v_exp_f32_e32 v96, v96
	v_exp_f32_e32 v97, v97
	v_exp_f32_e32 v98, v98
	v_exp_f32_e32 v99, v99
	v_exp_f32_e32 v100, v100
	v_exp_f32_e32 v101, v101
	v_exp_f32_e32 v102, v102
	v_exp_f32_e32 v103, v103
	v_add_f32_e32 v0, v0, v96
	v_add_f32_e32 v15, v15, v97
	v_add_f32_e32 v0, v0, v98
	v_add_f32_e32 v15, v15, v99
	v_add_f32_e32 v0, v0, v100
	v_add_f32_e32 v15, v15, v101
	v_add_f32_e32 v0, v0, v102
	v_add_f32_e32 v15, v15, v103
	v_cvt_pk_bf16_f32 v96, v96, v97
	v_cvt_pk_bf16_f32 v97, v98, v99
	v_cvt_pk_bf16_f32 v98, v100, v101
	v_cvt_pk_bf16_f32 v99, v102, v103
	ds_read_b64_tr_b16 v[230:231], v246 offset:20480
	ds_read_b64_tr_b16 v[232:233], v246 offset:22528
	ds_read_b64_tr_b16 v[234:235], v247 offset:20480
	ds_read_b64_tr_b16 v[236:237], v247 offset:22528
	ds_read_b64_tr_b16 v[238:239], v248 offset:20480
	ds_read_b64_tr_b16 v[240:241], v248 offset:22528
	ds_read_b64_tr_b16 v[242:243], v249 offset:20480
	ds_read_b64_tr_b16 v[244:245], v249 offset:22528
	s_waitcnt lgkmcnt(14)
	v_mfma_f32_32x32x16_bf16 v[64:79], v[2:5], v[96:99], v[64:79]
	s_waitcnt lgkmcnt(12)
	v_mfma_f32_32x32x16_bf16 v[48:63], v[6:9], v[96:99], v[48:63]
	s_waitcnt lgkmcnt(10)
	v_mfma_f32_32x32x16_bf16 v[32:47], v[10:13], v[96:99], v[32:47]
	s_waitcnt lgkmcnt(8)
	v_mfma_f32_32x32x16_bf16 v[16:31], v[144:147], v[96:99], v[16:31]
	v_exp_f32_e32 v104, v104
	v_exp_f32_e32 v105, v105
	v_exp_f32_e32 v106, v106
	v_exp_f32_e32 v107, v107
	v_exp_f32_e32 v108, v108
	v_exp_f32_e32 v109, v109
	v_exp_f32_e32 v110, v110
	v_exp_f32_e32 v111, v111
	v_add_f32_e32 v0, v0, v104
	v_add_f32_e32 v15, v15, v105
	v_add_f32_e32 v0, v0, v106
	v_add_f32_e32 v15, v15, v107
	v_add_f32_e32 v0, v0, v108
	v_add_f32_e32 v15, v15, v109
	v_add_f32_e32 v0, v0, v110
	v_add_f32_e32 v15, v15, v111
	v_cvt_pk_bf16_f32 v100, v104, v105
	v_cvt_pk_bf16_f32 v101, v106, v107
	v_cvt_pk_bf16_f32 v102, v108, v109
	v_cvt_pk_bf16_f32 v103, v110, v111
	s_nop 1
	s_waitcnt lgkmcnt(6)
	v_mfma_f32_32x32x16_bf16 v[64:79], v[230:233], v[100:103], v[64:79]
	s_waitcnt lgkmcnt(4)
	v_mfma_f32_32x32x16_bf16 v[48:63], v[234:237], v[100:103], v[48:63]
	s_waitcnt lgkmcnt(2)
	v_mfma_f32_32x32x16_bf16 v[32:47], v[238:241], v[100:103], v[32:47]
	s_waitcnt lgkmcnt(0)
	v_mfma_f32_32x32x16_bf16 v[16:31], v[242:245], v[100:103], v[16:31]
	v_add_f32_e32 v0, v0, v15
	v_add_f32_e32 v14, v14, v0
	s_branch .LBB0_101

; #define LAS __attribute__((address_space(3)))
; template <int DK>
; DI void attn_pass(const AttnSrc& s, const int q0, const float sc, LAS unsigned char* lds, f32x16 (&O)[4]) {
;     ...
;     if (64 * t <= qw0 + 31) {
;       LAS unsigned char* Kb = lds + buf * STG; LAS unsigned char* Vb = lds + buf * STG + KSZ;
;       f32x16 p0, p1;
;       constexpr int GS = (DK == 64) ? 4 : 2, NG = NS / GS;
;       bf16x8 kfa[2][GS], kfb[2][GS];
;       auto kload = [&](int g, int slot) {
; #pragma unroll
;         for (int j = 0; j < GS; ++j) { const int lc = 2 * (g * GS + j) + h; const int ph = (DK == 64) ? (lc ^ kx) : ((lc & ~7) | ((lc & 7) ^ kx));
;           kfa[slot][j] = *(const LAS bf16x8*)(Kb + krow + ph * 16); kfb[slot][j] = *(const LAS bf16x8*)(Kb + krow + 32 * ROWB + ph * 16); }
;       };
;       kload(0, 0);
; #pragma unroll
;       for (int g = 0; g < NG; ++g) {
;         if (g + 1 < NG) kload(g + 1, (g + 1) & 1);
;         __builtin_amdgcn_s_setprio(1);
; #pragma unroll
;         for (int j = 0; j < GS; ++j) {
;           if (g == 0 && j == 0) {
;             if (REL) {
;               p0 = __builtin_amdgcn_mfma_f32_32x32x16_bf16(kfa[0][0], qf[0], negm, 0, 0, 0);
;               p1 = __builtin_amdgcn_mfma_f32_32x32x16_bf16(kfb[0][0], qf[0], negm, 0, 0, 0);
;             } else {
;               f32x16 z;
; #pragma unroll
;               for (int jj = 0; jj < 16; ++jj) z[jj] = 0.f;
;               p0 = __builtin_amdgcn_mfma_f32_32x32x16_bf16(kfa[0][0], qf[0], z, 0, 0, 0);
;               p1 = __builtin_amdgcn_mfma_f32_32x32x16_bf16(kfb[0][0], qf[0], z, 0, 0, 0);
;             }
;           } else {
;             p0 = __builtin_amdgcn_mfma_f32_32x32x16_bf16(kfa[g & 1][j], qf[g * GS + j], p0, 0, 0, 0);
;             p1 = __builtin_amdgcn_mfma_f32_32x32x16_bf16(kfb[g & 1][j], qf[g * GS + j], p1, 0, 0, 0);
;           }
;         }
;         __builtin_amdgcn_s_setprio(0);
;       }
;       bf16x8 vf[2][4];
;       auto vload = [&](int vt, int slot) {
;         const int vcol = vrow + ((vt ^ vx) << 6);
; #pragma unroll
;         for (int ks = 0; ks < 4; ++ks) {
;           const s16x4 lo = __builtin_bit_cast(s16x4, __builtin_amdgcn_ds_read_tr16_b64_v4i16((LAS s16x4*)(Vb + vcol + ks * 16 * 256)));
;           const s16x4 hi = __builtin_bit_cast(s16x4, __builtin_amdgcn_ds_read_tr16_b64_v4i16((LAS s16x4*)(Vb + vcol + (ks * 16 + 8) * 256)));
.Ln192_act:
	s_mul_i32 s15, s54, 0xa000
	s_add_i32 s15, s15, 0
	v_add_u32_e32 v0, s15, v204
	v_add_u32_e32 v238, v0, v209
	v_add_u32_e32 v239, v0, v210
	v_add_u32_e32 v240, v0, v213
	v_add_u32_e32 v0, v0, v214
	ds_read_b128 v[66:69], v238
	ds_read_b128 v[70:73], v238 offset:12288
	ds_read_b128 v[146:149], v239
	ds_read_b128 v[150:153], v239 offset:12288
	ds_read_b128 v[154:157], v240
	ds_read_b128 v[158:161], v240 offset:12288
	ds_read_b128 v[220:223], v0
	ds_read_b128 v[224:227], v0 offset:12288
	s_waitcnt lgkmcnt(7)
	v_mfma_f32_32x32x16_bf16 v[82:97], v[66:69], v[98:101], 0
	s_waitcnt lgkmcnt(6)
	v_mfma_f32_32x32x16_bf16 v[66:81], v[70:73], v[98:101], 0
	s_waitcnt lgkmcnt(5)
	v_mfma_f32_32x32x16_bf16 v[82:97], v[146:149], v[102:105], v[82:97]
	s_waitcnt lgkmcnt(4)
	v_mfma_f32_32x32x16_bf16 v[66:81], v[150:153], v[102:105], v[66:81]
	ds_read_b128 v[146:149], v239 offset:128
	ds_read_b128 v[150:153], v239 offset:12416
	ds_read_b128 v[230:233], v238 offset:12416
	ds_read_b128 v[234:237], v238 offset:128
	s_waitcnt lgkmcnt(7)
	v_mfma_f32_32x32x16_bf16 v[82:97], v[154:157], v[106:109], v[82:97]
	s_waitcnt lgkmcnt(6)
	v_mfma_f32_32x32x16_bf16 v[66:81], v[158:161], v[106:109], v[66:81]
	s_waitcnt lgkmcnt(5)
	v_mfma_f32_32x32x16_bf16 v[82:97], v[220:223], v[110:113], v[82:97]
	s_waitcnt lgkmcnt(4)
	v_mfma_f32_32x32x16_bf16 v[66:81], v[224:227], v[110:113], v[66:81]
	ds_read_b128 v[154:157], v240 offset:128
	ds_read_b128 v[158:161], v240 offset:12416
	ds_read_b128 v[220:223], v0 offset:128
	ds_read_b128 v[224:227], v0 offset:12416
	s_waitcnt lgkmcnt(4)
	v_mfma_f32_32x32x16_bf16 v[82:97], v[234:237], v[114:117], v[82:97]
	v_mfma_f32_32x32x16_bf16 v[66:81], v[230:233], v[114:117], v[66:81]
	v_mfma_f32_32x32x16_bf16 v[82:97], v[146:149], v[118:121], v[82:97]
	v_mfma_f32_32x32x16_bf16 v[66:81], v[150:153], v[118:121], v[66:81]
	ds_read_b128 v[146:149], v239 offset:256
	ds_read_b128 v[150:153], v239 offset:12544
	ds_read_b128 v[230:233], v238 offset:12544
	ds_read_b128 v[234:237], v238 offset:256
	s_waitcnt lgkmcnt(7)
	v_mfma_f32_32x32x16_bf16 v[82:97], v[154:157], v[122:125], v[82:97]
	s_waitcnt lgkmcnt(6)
	v_mfma_f32_32x32x16_bf16 v[66:81], v[158:161], v[122:125], v[66:81]
	s_waitcnt lgkmcnt(5)
	v_mfma_f32_32x32x16_bf16 v[82:97], v[220:223], v[126:129], v[82:97]
	s_waitcnt lgkmcnt(4)
	v_mfma_f32_32x32x16_bf16 v[66:81], v[224:227], v[126:129], v[66:81]
	ds_read_b128 v[154:157], v240 offset:256
	ds_read_b128 v[158:161], v240 offset:12544
	ds_read_b128 v[220:223], v0 offset:256
	ds_read_b128 v[224:227], v0 offset:12544
	s_waitcnt lgkmcnt(4)
	v_mfma_f32_32x32x16_bf16 v[82:97], v[234:237], v[130:133], v[82:97]
	v_mfma_f32_32x32x16_bf16 v[66:81], v[230:233], v[130:133], v[66:81]
	v_mfma_f32_32x32x16_bf16 v[82:97], v[146:149], v[134:137], v[82:97]
	v_mfma_f32_32x32x16_bf16 v[66:81], v[150:153], v[134:137], v[66:81]
	s_waitcnt lgkmcnt(3)
	v_mfma_f32_32x32x16_bf16 v[82:97], v[154:157], v[138:141], v[82:97]
	s_waitcnt lgkmcnt(2)
	v_mfma_f32_32x32x16_bf16 v[66:81], v[158:161], v[138:141], v[66:81]
	s_waitcnt lgkmcnt(1)
	v_mfma_f32_32x32x16_bf16 v[82:97], v[220:223], v[142:145], v[82:97]
	s_waitcnt lgkmcnt(0)
	v_mfma_f32_32x32x16_bf16 v[66:81], v[224:227], v[142:145], v[66:81]
	v_add3_u32 v0, s15, v205, v206
	v_add3_u32 v239, v0, v207, v208
	v_add_u32_e32 v246, v239, v211
	v_add_u32_e32 v247, v239, v215
	v_add_u32_e32 v248, v239, v216
	v_add_u32_e32 v249, v239, v217
	ds_read_b64_tr_b16 v[146:147], v246 offset:24576
	ds_read_b64_tr_b16 v[148:149], v246 offset:26624
	ds_read_b64_tr_b16 v[150:151], v247 offset:24576
	ds_read_b64_tr_b16 v[152:153], v247 offset:26624
	ds_read_b64_tr_b16 v[154:155], v248 offset:24576
	ds_read_b64_tr_b16 v[156:157], v248 offset:26624
	ds_read_b64_tr_b16 v[158:159], v249 offset:24576
	ds_read_b64_tr_b16 v[160:161], v249 offset:26624
	s_cmp_le_i32 s55, s40
	s_cbranch_scc1 .Ln192_nomask
; template <int DK>
; DI void attn_pass(const AttnSrc& s, const int q0, const float sc, LAS unsigned char* lds, f32x16 (&O)[4]) {
;     ...
;       if (64 * t + 63 > qw0) {
;         const int qa = qw0 + r, kbase = 64 * t + 4 * h;
; #pragma unroll
;         for (int j = 0; j < 16; ++j) { const int kv = kbase + (j & 3) + 8 * (j >> 2); if (kv > qa) p0[j] = -INFINITY; if (kv + 32 > qa) p1[j] = -INFINITY; }
;       }
;       asm volatile("s_nop 15\n\ts_nop 7" : "+v"(p0), "+v"(p1));
	v_add_u32_e32 v0, s55, v212
	v_subrev_u32_e32 v222, 31, v0
	v_subrev_u32_e32 v221, 63, v0
	v_cmp_le_i32_e32 vcc, v222, v167
	s_nop 1
	v_cndmask_b32_e32 v66, v201, v66, vcc
	v_cmp_lt_i32_e32 vcc, v221, v167
	s_nop 1
	v_cndmask_b32_e32 v83, v201, v83, vcc
	v_cmp_le_i32_e32 vcc, v221, v167
	v_subrev_u32_e32 v221, 30, v0
	s_nop 0
	v_cndmask_b32_e32 v82, v201, v82, vcc
	v_cmp_le_i32_e32 vcc, v221, v167
	v_subrev_u32_e32 v221, 61, v0
	s_nop 0
	v_cndmask_b32_e32 v67, v201, v67, vcc
	v_cmp_le_i32_e32 vcc, v221, v167
	v_subrev_u32_e32 v221, 29, v0
	s_nop 0
	v_cndmask_b32_e32 v84, v201, v84, vcc
	v_cmp_le_i32_e32 vcc, v221, v167
	v_subrev_u32_e32 v221, 60, v0
	s_nop 0
	v_cndmask_b32_e32 v68, v201, v68, vcc
	v_cmp_le_i32_e32 vcc, v221, v167
	v_subrev_u32_e32 v221, 28, v0
	s_nop 0
	v_cndmask_b32_e32 v85, v201, v85, vcc
	v_cmp_le_i32_e32 vcc, v221, v167
	v_subrev_u32_e32 v221, 55, v0
	s_nop 0
	v_cndmask_b32_e32 v69, v201, v69, vcc
	v_cmp_le_i32_e32 vcc, v221, v167
	v_subrev_u32_e32 v221, 23, v0
	s_nop 0
	v_cndmask_b32_e32 v86, v201, v86, vcc
	v_cmp_le_i32_e32 vcc, v221, v167
	v_subrev_u32_e32 v221, 54, v0
	s_nop 0
	v_cndmask_b32_e32 v70, v201, v70, vcc
	v_cmp_le_i32_e32 vcc, v221, v167
	v_subrev_u32_e32 v221, 22, v0
	s_nop 0
	v_cndmask_b32_e32 v87, v201, v87, vcc
	v_cmp_le_i32_e32 vcc, v221, v167
	v_subrev_u32_e32 v221, 53, v0
	s_nop 0
	v_cndmask_b32_e32 v71, v201, v71, vcc
	v_cmp_le_i32_e32 vcc, v221, v167
	v_subrev_u32_e32 v221, 21, v0
	s_nop 0
	v_cndmask_b32_e32 v88, v201, v88, vcc
	v_cmp_le_i32_e32 vcc, v221, v167
	v_subrev_u32_e32 v221, 52, v0
	s_nop 0
	v_cndmask_b32_e32 v72, v201, v72, vcc
	v_cmp_le_i32_e32 vcc, v221, v167
	v_subrev_u32_e32 v221, 20, v0
	s_nop 0
	v_cndmask_b32_e32 v89, v201, v89, vcc
	v_cmp_le_i32_e32 vcc, v221, v167
	v_subrev_u32_e32 v221, 47, v0
	s_nop 0
	v_cndmask_b32_e32 v73, v201, v73, vcc
	v_cmp_le_i32_e32 vcc, v221, v167
	v_add_u32_e32 v221, -15, v0
	s_nop 0
	v_cndmask_b32_e32 v90, v201, v90, vcc
	v_cmp_le_i32_e32 vcc, v221, v167
	v_subrev_u32_e32 v221, 46, v0
	s_nop 0
	v_cndmask_b32_e32 v74, v201, v74, vcc
	v_cmp_le_i32_e32 vcc, v221, v167
	v_add_u32_e32 v221, -14, v0
	s_nop 0
	v_cndmask_b32_e32 v91, v201, v91, vcc
	v_cmp_le_i32_e32 vcc, v221, v167
	v_subrev_u32_e32 v221, 45, v0
	s_nop 0
	v_cndmask_b32_e32 v75, v201, v75, vcc
	v_cmp_le_i32_e32 vcc, v221, v167
	v_add_u32_e32 v221, -13, v0
	s_nop 0
	v_cndmask_b32_e32 v92, v201, v92, vcc
	v_cmp_le_i32_e32 vcc, v221, v167
	v_subrev_u32_e32 v221, 44, v0
	s_nop 0
	v_cndmask_b32_e32 v76, v201, v76, vcc
	v_cmp_le_i32_e32 vcc, v221, v167
	v_add_u32_e32 v221, -12, v0
	s_nop 0
	v_cndmask_b32_e32 v93, v201, v93, vcc
	v_cmp_le_i32_e32 vcc, v221, v167
	v_subrev_u32_e32 v221, 39, v0
	s_nop 0
	v_cndmask_b32_e32 v77, v201, v77, vcc
	v_cmp_le_i32_e32 vcc, v221, v167
	v_add_u32_e32 v221, -7, v0
	s_nop 0
	v_cndmask_b32_e32 v94, v201, v94, vcc
	v_cmp_le_i32_e32 vcc, v221, v167
	v_subrev_u32_e32 v221, 38, v0
	s_nop 0
	v_cndmask_b32_e32 v78, v201, v78, vcc
	v_cmp_le_i32_e32 vcc, v221, v167
	v_add_u32_e32 v221, -6, v0
	s_nop 0
	v_cndmask_b32_e32 v95, v201, v95, vcc
	v_cmp_le_i32_e32 vcc, v221, v167
	v_subrev_u32_e32 v221, 37, v0
	s_nop 0
	v_cndmask_b32_e32 v79, v201, v79, vcc
	v_cmp_le_i32_e32 vcc, v221, v167
	v_add_u32_e32 v221, -5, v0
	s_nop 0
	v_cndmask_b32_e32 v96, v201, v96, vcc
	v_cmp_le_i32_e32 vcc, v221, v167
	v_subrev_u32_e32 v221, 36, v0
	v_add_u32_e32 v0, -4, v0
	v_cndmask_b32_e32 v80, v201, v80, vcc
	v_cmp_le_i32_e32 vcc, v221, v167
	s_nop 1
	v_cndmask_b32_e32 v97, v201, v97, vcc
	v_cmp_le_i32_e32 vcc, v0, v167
	s_nop 1
	v_cndmask_b32_e32 v81, v201, v81, vcc

; DI unsigned cvt_pk_bf16(float lo, float hi) { unsigned r; asm volatile("v_cvt_pk_bf16_f32 %0, %1, %2" : "=v"(r) : "v"(lo), "v"(hi)); return r; }
; template <int DK>
; DI void attn_pass(const AttnSrc& s, const int q0, const float sc, LAS unsigned char* lds, f32x16 (&O)[4]) {
;     ...
; #pragma unroll
;         for (int j = 0; j < 16; ++j) { p0[j] = __builtin_amdgcn_exp2f(p0[j] * sc - mrun); p1[j] = __builtin_amdgcn_exp2f(p1[j] * sc - mrun); rs += p0[j] + p1[j]; }
;       }
;       lrun += rs;
;       bf16x8 pb[4];
;       { u32x4 w;
;         w.x = cvt_pk_bf16(p0[0], p0[1]); w.y = cvt_pk_bf16(p0[2], p0[3]); w.z = cvt_pk_bf16(p0[4], p0[5]); w.w = cvt_pk_bf16(p0[6], p0[7]); pb[0] = __builtin_bit_cast(bf16x8, w);
;         w.x = cvt_pk_bf16(p0[8], p0[9]); w.y = cvt_pk_bf16(p0[10], p0[11]); w.z = cvt_pk_bf16(p0[12], p0[13]); w.w = cvt_pk_bf16(p0[14], p0[15]); pb[1] = __builtin_bit_cast(bf16x8, w);
;         w.x = cvt_pk_bf16(p1[0], p1[1]); w.y = cvt_pk_bf16(p1[2], p1[3]); w.z = cvt_pk_bf16(p1[4], p1[5]); w.w = cvt_pk_bf16(p1[6], p1[7]); pb[2] = __builtin_bit_cast(bf16x8, w);
;         w.x = cvt_pk_bf16(p1[8], p1[9]); w.y = cvt_pk_bf16(p1[10], p1[11]); w.z = cvt_pk_bf16(p1[12], p1[13]); w.w = cvt_pk_bf16(p1[14], p1[15]); pb[3] = __builtin_bit_cast(bf16x8, w); }
; #pragma unroll
;       for (int vt = 0; vt < 4; ++vt) {
;         if (vt + 1 < 4) vload(vt + 1, (vt + 1) & 1);
;         __builtin_amdgcn_s_setprio(1);
; #pragma unroll
;         for (int ks = 0; ks < 4; ++ks) O[vt] = __builtin_amdgcn_mfma_f32_32x32x16_bf16(vf[vt & 1][ks], pb[ks], O[vt], 0, 0, 0);
;         __builtin_amdgcn_s_setprio(0);
;       }
.Ln192_exp:
	v_fma_f32 v82, v82, s61, -v219
	v_fma_f32 v83, v83, s61, -v219
	v_fma_f32 v84, v84, s61, -v219
	v_fma_f32 v85, v85, s61, -v219
	v_fma_f32 v86, v86, s61, -v219
	v_fma_f32 v87, v87, s61, -v219
	v_fma_f32 v88, v88, s61, -v219
	v_fma_f32 v89, v89, s61, -v219
	v_exp_f32_e32 v82, v82
	v_exp_f32_e32 v83, v83
	v_exp_f32_e32 v84, v84
	v_exp_f32_e32 v85, v85
	v_exp_f32_e32 v86, v86
	v_exp_f32_e32 v87, v87
	v_exp_f32_e32 v88, v88
	v_exp_f32_e32 v89, v89
	v_add_f32_e32 v0, v82, v83
	v_add_f32_e32 v238, v84, v85
	v_add_f32_e32 v0, v0, v86
	v_add_f32_e32 v238, v238, v87
	v_add_f32_e32 v0, v0, v88
	v_add_f32_e32 v238, v238, v89
	v_cvt_pk_bf16_f32 v82, v82, v83
	v_cvt_pk_bf16_f32 v83, v84, v85
	v_cvt_pk_bf16_f32 v84, v86, v87
	v_cvt_pk_bf16_f32 v85, v88, v89
	ds_read_b64_tr_b16 v[220:221], v246 offset:28672
	ds_read_b64_tr_b16 v[222:223], v246 offset:30720
	ds_read_b64_tr_b16 v[224:225], v247 offset:28672
	ds_read_b64_tr_b16 v[226:227], v247 offset:30720
	ds_read_b64_tr_b16 v[230:231], v248 offset:28672
	ds_read_b64_tr_b16 v[232:233], v248 offset:30720
	ds_read_b64_tr_b16 v[234:235], v249 offset:28672
	ds_read_b64_tr_b16 v[236:237], v249 offset:30720
	s_waitcnt lgkmcnt(14)
	v_mfma_f32_32x32x16_bf16 v[50:65], v[146:149], v[82:85], v[50:65]
	s_waitcnt lgkmcnt(12)
	v_mfma_f32_32x32x16_bf16 v[34:49], v[150:153], v[82:85], v[34:49]
	s_waitcnt lgkmcnt(10)
	v_mfma_f32_32x32x16_bf16 v[18:33], v[154:157], v[82:85], v[18:33]
	s_waitcnt lgkmcnt(8)
	v_mfma_f32_32x32x16_bf16 v[2:17], v[158:161], v[82:85], v[2:17]
	v_fma_f32 v90, v90, s61, -v219
	v_fma_f32 v91, v91, s61, -v219
	v_fma_f32 v92, v92, s61, -v219
	v_fma_f32 v93, v93, s61, -v219
	v_fma_f32 v94, v94, s61, -v219
	v_fma_f32 v95, v95, s61, -v219
	v_fma_f32 v96, v96, s61, -v219
	v_fma_f32 v97, v97, s61, -v219
	v_exp_f32_e32 v90, v90
	v_exp_f32_e32 v91, v91
	v_exp_f32_e32 v92, v92
	v_exp_f32_e32 v93, v93
	v_exp_f32_e32 v94, v94
	v_exp_f32_e32 v95, v95
	v_exp_f32_e32 v96, v96
	v_exp_f32_e32 v97, v97
	v_add_f32_e32 v0, v0, v90
	v_add_f32_e32 v238, v238, v91
	v_add_f32_e32 v0, v0, v92
	v_add_f32_e32 v238, v238, v93
	v_add_f32_e32 v0, v0, v94
	v_add_f32_e32 v238, v238, v95
	v_add_f32_e32 v0, v0, v96
	v_add_f32_e32 v238, v238, v97
	v_cvt_pk_bf16_f32 v86, v90, v91
	v_cvt_pk_bf16_f32 v87, v92, v93
	v_cvt_pk_bf16_f32 v88, v94, v95
	v_cvt_pk_bf16_f32 v89, v96, v97
	ds_read_b64_tr_b16 v[146:147], v246 offset:32768
	ds_read_b64_tr_b16 v[148:149], v246 offset:34816
	ds_read_b64_tr_b16 v[150:151], v247 offset:32768
	ds_read_b64_tr_b16 v[152:153], v247 offset:34816
	ds_read_b64_tr_b16 v[154:155], v248 offset:32768
	ds_read_b64_tr_b16 v[156:157], v248 offset:34816
	ds_read_b64_tr_b16 v[158:159], v249 offset:32768
	ds_read_b64_tr_b16 v[160:161], v249 offset:34816
	s_waitcnt lgkmcnt(14)
	v_mfma_f32_32x32x16_bf16 v[50:65], v[220:223], v[86:89], v[50:65]
	s_waitcnt lgkmcnt(12)
	v_mfma_f32_32x32x16_bf16 v[34:49], v[224:227], v[86:89], v[34:49]
	s_waitcnt lgkmcnt(10)
	v_mfma_f32_32x32x16_bf16 v[18:33], v[230:233], v[86:89], v[18:33]
	s_waitcnt lgkmcnt(8)
	v_mfma_f32_32x32x16_bf16 v[2:17], v[234:237], v[86:89], v[2:17]
	v_fma_f32 v66, v66, s61, -v219
	v_fma_f32 v67, v67, s61, -v219
	v_fma_f32 v68, v68, s61, -v219
	v_fma_f32 v69, v69, s61, -v219
	v_fma_f32 v70, v70, s61, -v219
	v_fma_f32 v71, v71, s61, -v219
	v_fma_f32 v72, v72, s61, -v219
	v_fma_f32 v73, v73, s61, -v219
	v_exp_f32_e32 v66, v66
	v_exp_f32_e32 v67, v67
	v_exp_f32_e32 v68, v68
	v_exp_f32_e32 v69, v69
	v_exp_f32_e32 v70, v70
	v_exp_f32_e32 v71, v71
	v_exp_f32_e32 v72, v72
	v_exp_f32_e32 v73, v73
	v_add_f32_e32 v0, v0, v66
	v_add_f32_e32 v238, v238, v67
	v_add_f32_e32 v0, v0, v68
	v_add_f32_e32 v238, v238, v69
	v_add_f32_e32 v0, v0, v70
	v_add_f32_e32 v238, v238, v71
	v_add_f32_e32 v0, v0, v72
	v_add_f32_e32 v238, v238, v73
	v_cvt_pk_bf16_f32 v66, v66, v67
	v_cvt_pk_bf16_f32 v67, v68, v69
	v_cvt_pk_bf16_f32 v68, v70, v71
	v_cvt_pk_bf16_f32 v69, v72, v73
	ds_read_b64_tr_b16 v[220:221], v246 offset:36864
	ds_read_b64_tr_b16 v[222:223], v246 offset:38912
	ds_read_b64_tr_b16 v[224:225], v247 offset:36864
	ds_read_b64_tr_b16 v[226:227], v247 offset:38912
	ds_read_b64_tr_b16 v[230:231], v248 offset:36864
	ds_read_b64_tr_b16 v[232:233], v248 offset:38912
	ds_read_b64_tr_b16 v[234:235], v249 offset:36864
	ds_read_b64_tr_b16 v[236:237], v249 offset:38912
	s_waitcnt lgkmcnt(14)
	v_mfma_f32_32x32x16_bf16 v[50:65], v[146:149], v[66:69], v[50:65]
	s_waitcnt lgkmcnt(12)
	v_mfma_f32_32x32x16_bf16 v[34:49], v[150:153], v[66:69], v[34:49]
	s_waitcnt lgkmcnt(10)
	v_mfma_f32_32x32x16_bf16 v[18:33], v[154:157], v[66:69], v[18:33]
	s_waitcnt lgkmcnt(8)
	v_mfma_f32_32x32x16_bf16 v[2:17], v[158:161], v[66:69], v[2:17]
	v_fma_f32 v74, v74, s61, -v219
	v_fma_f32 v75, v75, s61, -v219
	v_fma_f32 v76, v76, s61, -v219
	v_fma_f32 v77, v77, s61, -v219
	v_fma_f32 v78, v78, s61, -v219
	v_fma_f32 v79, v79, s61, -v219
	v_fma_f32 v80, v80, s61, -v219
	v_fma_f32 v81, v81, s61, -v219
	v_exp_f32_e32 v74, v74
	v_exp_f32_e32 v75, v75
	v_exp_f32_e32 v76, v76
	v_exp_f32_e32 v77, v77
	v_exp_f32_e32 v78, v78
	v_exp_f32_e32 v79, v79
	v_exp_f32_e32 v80, v80
	v_exp_f32_e32 v81, v81
	v_add_f32_e32 v0, v0, v74
	v_add_f32_e32 v238, v238, v75
	v_add_f32_e32 v0, v0, v76
	v_add_f32_e32 v238, v238, v77
	v_add_f32_e32 v0, v0, v78
	v_add_f32_e32 v238, v238, v79
	v_add_f32_e32 v0, v0, v80
	v_add_f32_e32 v238, v238, v81
	v_cvt_pk_bf16_f32 v70, v74, v75
	v_cvt_pk_bf16_f32 v71, v76, v77
	v_cvt_pk_bf16_f32 v72, v78, v79
	v_cvt_pk_bf16_f32 v73, v80, v81
	s_nop 1
	s_waitcnt lgkmcnt(6)
	v_mfma_f32_32x32x16_bf16 v[50:65], v[220:223], v[70:73], v[50:65]
	s_waitcnt lgkmcnt(4)
	v_mfma_f32_32x32x16_bf16 v[34:49], v[224:227], v[70:73], v[34:49]
	s_waitcnt lgkmcnt(2)
	v_mfma_f32_32x32x16_bf16 v[18:33], v[230:233], v[70:73], v[18:33]
	s_waitcnt lgkmcnt(0)
	v_mfma_f32_32x32x16_bf16 v[2:17], v[234:237], v[70:73], v[2:17]
	v_add_f32_e32 v0, v0, v238
	v_add_f32_e32 v218, v218, v0
	s_branch .LBB0_137
; DI float bf_lo(unsigned w) { return __uint_as_float(w << 16); }
; DI float bf_hi(unsigned w) { return __uint_as_float(w & 0xffff0000u); }
; DI float bf2f(bf16_t b) { return __uint_as_float(((unsigned)b) << 16); }
; DI int tid_fresh() { int t = threadIdx.x; asm volatile("" : "+v"(t)); return t; }
; DI void phase_prep(KParams P, bf16_t* lat) {
;   const int lane = tid_fresh() & 63, wid = tid_fresh() >> 6;
;   for (int row = blockIdx.x * 8 + wid; row < T_TOK; row += gridDim.x * 8) {
;     bf16_t* p = lat + (size_t)row * 1536;
;     u32x2 a[3], b[2]; float s1 = 0.f, s2 = 0.f;
; #pragma unroll
;     for (int j = 0; j < 3; ++j) { a[j] = *(const u32x2*)(p + (j * 64 + lane) * 4); const float x0 = bf_lo(a[j].x), x1 = bf_hi(a[j].x), x2 = bf_lo(a[j].y), x3 = bf_hi(a[j].y); s1 += x0 * x0 + x1 * x1 + x2 * x2 + x3 * x3; }
; #pragma unroll
;     for (int j = 0; j < 2; ++j) { b[j] = *(const u32x2*)(p + 768 + (j * 64 + lane) * 4); const float x0 = bf_lo(b[j].x), x1 = bf_hi(b[j].x), x2 = bf_lo(b[j].y), x3 = bf_hi(b[j].y); s2 += x0 * x0 + x1 * x1 + x2 * x2 + x3 * x3; }
;     const float kr = bf2f(p[1280 + lane]);
.LBB0_149:
	s_setprio 0
	s_andn2_b64 vcc, exec, s[50:51]
	s_movk_i32 s17, 0x6000
	s_mov_b32 s23, 0x8007000
	s_movk_i32 s40, 0x7000
	v_readlane_b32 s12, v250, 25
	v_readlane_b32 s13, v250, 26
	s_cbranch_vccnz .LBB0_298
	s_cmp_lt_i32 s12, 2
	s_mov_b64 s[4:5], -1
	s_cbranch_scc1 .LBB0_157
	s_cmp_eq_u32 s12, 2
	s_cbranch_scc0 .LBB0_156
	v_mov_b32_e32 v0, v163
	v_mov_b32_e32 v2, v163
	v_readlane_b32 s3, v251, 5
	v_ashrrev_i32_e32 v2, 6, v2
	s_waitcnt lgkmcnt(0)
	v_add_u32_e32 v6, s3, v2
	v_cmp_gt_i32_e32 vcc, s78, v6
	s_and_saveexec_b64 s[4:5], vcc
	s_cbranch_execz .LBB0_155
	v_cmp_lt_i32_e32 vcc, v193, v192
	s_load_dwordx2 s[8:9], s[0:1], 0x58
	v_and_b32_e32 v2, 63, v0
	v_cndmask_b32_e32 v3, v191, v193, vcc
	v_cmp_lt_i32_e32 vcc, v194, v192
	v_lshlrev_b32_e32 v9, 2, v3
	s_add_u32 s6, s48, 0x6000000
	v_cndmask_b32_e32 v3, v191, v194, vcc
	v_cmp_lt_i32_e32 vcc, v195, v192
	v_lshlrev_b32_e32 v42, 2, v3
	s_addc_u32 s7, s49, 0
	v_cndmask_b32_e32 v3, v191, v195, vcc
	v_cmp_lt_i32_e32 vcc, v196, v192
	v_lshlrev_b32_e32 v43, 2, v3
	v_lshlrev_b32_e32 v8, 2, v2
	v_cndmask_b32_e32 v3, v191, v196, vcc
	v_cmp_lt_i32_e32 vcc, v197, v192
	v_lshlrev_b32_e32 v44, 2, v3
	v_lshlrev_b32_e32 v12, 1, v2
	v_cndmask_b32_e32 v3, v191, v197, vcc
	v_cmp_lt_i32_e32 vcc, v198, v192
	v_lshlrev_b32_e32 v45, 2, v3
	s_nop 0
	v_cndmask_b32_e32 v3, v191, v198, vcc
	v_lshlrev_b32_e32 v46, 2, v3
	v_lshlrev_b32_e32 v3, 1, v0
	v_and_b32_e32 v4, 62, v3
	v_bfe_u32 v0, v0, 5, 1
	v_or_b32_e32 v16, v4, v0
	v_lshlrev_b32_e32 v0, 4, v2
	v_cmp_gt_u32_e32 vcc, 32, v2
	s_waitcnt lgkmcnt(0)
	v_lshl_add_u64 v[10:11], s[8:9], 0, v[0:1]
	s_mov_b64 s[8:9], 0
	v_lshlrev_b32_e32 v14, 2, v4
	v_lshlrev_b32_e32 v16, 1, v16
